# grid barrier: leader waits only for its TOP atomic (vmcnt 1), its L1 invalidate completes after it has released the others
# speedup vs baseline: 1.0238x; 1.0003x over previous
.LBB0_588:
	s_or_b64 exec, exec, s[4:5]
	buffer_inv sc1
	s_waitcnt vmcnt(1)
	v_readfirstlane_b32 s2, v3
	v_sub_u32_e32 v4, 0, v2
	s_mov_b64 s[4:5], -1
	v_add_u32_e32 v3, s2, v0
	v_cvt_f32_u32_e32 v0, v2
	v_readlane_b32 s2, v215, 26
	v_readlane_b32 s3, v215, 27
	v_rcp_iflag_f32_e32 v0, v0
	s_nop 0
	v_mul_f32_e32 v0, 0x4f7ffffe, v0
	v_cvt_u32_f32_e32 v0, v0
	v_mul_lo_u32 v4, v4, v0
	v_mul_hi_u32 v4, v0, v4
	v_add_u32_e32 v0, v0, v4
	v_mul_hi_u32 v0, v3, v0
	v_mul_lo_u32 v4, v0, v2
	v_sub_u32_e32 v4, v3, v4
	v_cmp_ge_u32_e32 vcc, v4, v2
	v_add_u32_e32 v5, 1, v0
	v_add_u32_e32 v3, 1, v3
	v_cndmask_b32_e32 v0, v0, v5, vcc
	v_sub_u32_e32 v5, v4, v2
	v_cndmask_b32_e32 v4, v4, v5, vcc
	v_cmp_ge_u32_e32 vcc, v4, v2
	v_add_u32_e32 v4, 1, v0
	s_nop 0
	v_cndmask_b32_e32 v0, v0, v4, vcc
	v_mul_lo_u32 v4, v2, v0
	v_add_u32_e32 v2, v4, v2
	v_cmp_ne_u32_e32 vcc, v3, v2
	v_mov_b64_e32 v[2:3], s[2:3]
	s_mov_b32 s16, 0
	s_and_saveexec_b64 s[2:3], vcc
	s_cbranch_execz .LBB0_600
	s_mov_b32 s16, 1
	v_readlane_b32 s4, v215, 26
	v_readlane_b32 s5, v215, 27
	s_mov_b64 s[6:7], 0
	s_nop 3
	global_load_dword v2, v1, s[4:5] sc1
	s_waitcnt vmcnt(0)
	v_cmp_eq_u32_e32 vcc, v2, v0
	s_and_saveexec_b64 s[4:5], vcc
	s_cbranch_execz .LBB0_599
	s_mov_b32 s16, 1
	s_branch .LBB0_592
